# grid barrier without the cross-XCD top counter: each XCD's last arriver adds 1 to all XCD generation words after its write-back; every workgroup waits for its own XCD word to reach (gen+1)*nXCD (one r
# speedup vs baseline: 1.0146x; 1.0095x over previous
; __device__ __forceinline__ unsigned xb_ld(unsigned* p)              { return __hip_atomic_load(p, __ATOMIC_RELAXED, __HIP_MEMORY_SCOPE_AGENT); }
; __device__ __forceinline__ unsigned xb_add(unsigned* p, unsigned v) { return __hip_atomic_fetch_add(p, v, __ATOMIC_RELAXED, __HIP_MEMORY_SCOPE_AGENT); }
; #define XB_SPIN(cond, bar) do { unsigned _sp = 0; while (cond) { __builtin_amdgcn_s_sleep(1); \
;     if ((++_sp & 255u) == 0u) { if (xb_ld(&(bar)[XB_TMO])) break; if (_sp > XB_SPIN_CAP) { atomicAdd(&(bar)[XB_TMO], 1u); break; } } } } while (0)
; __device__ __forceinline__ void xcd_barrier(const XcdBarrier& b) {
;     ...
;         const unsigned old = xb_add(&bar[XB_XSUB(b.x)], 1u);
;         const unsigned gen = old / nloc;
;         if (old + 1u == (gen + 1u) * nloc) {
;             __builtin_amdgcn_fence(__ATOMIC_RELEASE, "agent");
;             asm volatile("s_waitcnt vmcnt(0)" ::: "memory");
;             const unsigned og = xb_add(&bar[XB_TOP], 1u);
;             const unsigned tg = og / nx;
;             if (og + 1u == (tg + 1u) * nx) xb_add(&bar[XB_TOPGEN], 1u);
;             else XB_SPIN(xb_ld(&bar[XB_TOPGEN]) == tg, bar);
;             __builtin_amdgcn_fence(__ATOMIC_ACQUIRE, "agent");
;             xb_add(&bar[XB_XGEN(b.x)], 1u);
;             asm volatile("s_waitcnt vmcnt(0)" ::: "memory");
;         } else {
;             XB_SPIN(xb_ld(&bar[XB_XGEN(b.x)]) == gen, bar);
.LBB0_145:
	s_or_b64 exec, exec, s[10:11]
	v_cvt_f32_u32_e32 v5, v3
	s_waitcnt vmcnt(0)
	v_readfirstlane_b32 s8, v4
	v_sub_u32_e32 v4, 0, v3
	v_rcp_iflag_f32_e32 v5, v5
	v_add_u32_e32 v6, s8, v2
	v_mul_f32_e32 v5, 0x4f7ffffe, v5
	v_cvt_u32_f32_e32 v5, v5
	v_mul_lo_u32 v2, v4, v5
	v_mul_hi_u32 v2, v5, v2
	v_add_u32_e32 v2, v5, v2
	v_mul_hi_u32 v2, v6, v2
	v_mul_lo_u32 v4, v2, v3
	v_sub_u32_e32 v4, v6, v4
	v_add_u32_e32 v5, 1, v2
	v_cmp_ge_u32_e32 vcc, v4, v3
	s_nop 1
	v_cndmask_b32_e32 v2, v2, v5, vcc
	v_sub_u32_e32 v5, v4, v3
	v_cndmask_b32_e32 v4, v4, v5, vcc
	v_add_u32_e32 v5, 1, v2
	v_cmp_ge_u32_e32 vcc, v4, v3
	v_add_u32_e32 v4, 1, v6
	s_nop 0
	v_cndmask_b32_e32 v2, v2, v5, vcc
	v_mul_lo_u32 v5, v3, v2
	v_add_u32_e32 v3, v5, v3
	v_mad_u32_u24 v255, v2, v1, v1
	v_cmp_ne_u32_e32 vcc, v4, v3
	s_and_saveexec_b64 s[8:9], vcc
	s_xor_b64 s[8:9], exec, s[8:9]
	s_cbranch_execz .LBB0_159
	buffer_inv sc1
	s_add_i32 s10, s28, 0x900
	s_mov_b32 s11, 0
	s_lshl_b64 s[10:11], s[10:11], 2
	s_add_u32 s14, s26, s10
	s_addc_u32 s15, s27, s11
	s_waitcnt lgkmcnt(0)
	v_mov_b32_e32 v1, 0
	global_load_dword v3, v1, s[14:15] sc1
	s_waitcnt vmcnt(0)
	v_cmp_lt_u32_e32 vcc, v3, v255
	s_and_saveexec_b64 s[10:11], vcc
	s_cbranch_execz .LBB0_158
	s_add_u32 s12, s6, 0xc0200
	s_addc_u32 s13, s7, 0
	s_mov_b32 s29, 1
	s_mov_b64 s[16:17], 0
	s_branch .LBB0_149

; __device__ __forceinline__ unsigned xb_ld(unsigned* p)              { return __hip_atomic_load(p, __ATOMIC_RELAXED, __HIP_MEMORY_SCOPE_AGENT); }
; #define XB_SPIN(cond, bar) do { unsigned _sp = 0; while (cond) { __builtin_amdgcn_s_sleep(1); \
;     if ((++_sp & 255u) == 0u) { if (xb_ld(&(bar)[XB_TMO])) break; if (_sp > XB_SPIN_CAP) { atomicAdd(&(bar)[XB_TMO], 1u); break; } } } } while (0)
; __device__ __forceinline__ void xcd_barrier(const XcdBarrier& b) {
;     ...
;             XB_SPIN(xb_ld(&bar[XB_XGEN(b.x)]) == gen, bar);
.LBB0_151:
	global_load_dword v3, v1, s[14:15] sc1
	s_add_i32 s29, s29, 1
	s_mov_b64 s[22:23], -1
	s_waitcnt vmcnt(0)
	v_cmp_ge_u32_e32 vcc, v3, v255
	s_orn2_b64 s[20:21], vcc, exec
	s_branch .LBB0_148

; __device__ __forceinline__ unsigned xb_ld(unsigned* p)              { return __hip_atomic_load(p, __ATOMIC_RELAXED, __HIP_MEMORY_SCOPE_AGENT); }
; __device__ __forceinline__ unsigned xb_add(unsigned* p, unsigned v) { return __hip_atomic_fetch_add(p, v, __ATOMIC_RELAXED, __HIP_MEMORY_SCOPE_AGENT); }
; #define XB_SPIN(cond, bar) do { unsigned _sp = 0; while (cond) { __builtin_amdgcn_s_sleep(1); \
;     if ((++_sp & 255u) == 0u) { if (xb_ld(&(bar)[XB_TMO])) break; if (_sp > XB_SPIN_CAP) { atomicAdd(&(bar)[XB_TMO], 1u); break; } } } } while (0)
; __device__ __forceinline__ void xcd_barrier(const XcdBarrier& b) {
;     ...
;         if (old + 1u == (gen + 1u) * nloc) {
;             __builtin_amdgcn_fence(__ATOMIC_RELEASE, "agent");
;             asm volatile("s_waitcnt vmcnt(0)" ::: "memory");
;             const unsigned og = xb_add(&bar[XB_TOP], 1u);
;             const unsigned tg = og / nx;
;             if (og + 1u == (tg + 1u) * nx) xb_add(&bar[XB_TOPGEN], 1u);
;             else XB_SPIN(xb_ld(&bar[XB_TOPGEN]) == tg, bar);
;             __builtin_amdgcn_fence(__ATOMIC_ACQUIRE, "agent");
.LBB0_159:
	s_andn2_saveexec_b64 s[8:9], s[8:9]
	s_cbranch_execz .LBB0_179
	s_mov_b64 s[8:9], exec
	buffer_wbl2 sc1
	buffer_inv sc1
	s_waitcnt lgkmcnt(0)
	s_waitcnt vmcnt(0)
	v_mbcnt_lo_u32_b32 v2, s8, 0
	v_mbcnt_hi_u32_b32 v2, s9, v2
	v_cmp_eq_u32_e32 vcc, 0, v2
	s_and_saveexec_b64 s[10:11], vcc
	s_cbranch_execz .LBB0_162
	s_bcnt1_i32_b64 s8, s[8:9]
	v_mov_b32_e32 v3, 0xc2400
	v_mov_b32_e32 v4, s8
	global_atomic_add v3, v4, s[6:7]
	global_atomic_add v3, v4, s[6:7] offset:256
	global_atomic_add v3, v4, s[6:7] offset:512
	global_atomic_add v3, v4, s[6:7] offset:768
	global_atomic_add v3, v4, s[6:7] offset:1024
	global_atomic_add v3, v4, s[6:7] offset:1280
	global_atomic_add v3, v4, s[6:7] offset:1536
	global_atomic_add v3, v4, s[6:7] offset:1792
	global_atomic_add v3, v4, s[6:7] offset:2048
	global_atomic_add v3, v4, s[6:7] offset:2304
	global_atomic_add v3, v4, s[6:7] offset:2560
	global_atomic_add v3, v4, s[6:7] offset:2816
	global_atomic_add v3, v4, s[6:7] offset:3072
	global_atomic_add v3, v4, s[6:7] offset:3328
	global_atomic_add v3, v4, s[6:7] offset:3584
	global_atomic_add v3, v4, s[6:7] offset:3840
.LBB0_162:
	s_or_b64 exec, exec, s[10:11]
	v_cvt_f32_u32_e32 v4, v1
	s_waitcnt vmcnt(0)
	v_readfirstlane_b32 s8, v3
	s_add_i32 s10, s28, 0x900
	s_mov_b32 s11, 0
	s_lshl_b64 s[10:11], s[10:11], 2
	s_add_u32 s10, s26, s10
	s_addc_u32 s11, s27, s11
	v_rcp_iflag_f32_e32 v4, v4
	v_add_u32_e32 v2, s8, v2
	v_add_u32_e32 v5, 1, v2
	s_mov_b64 s[12:13], -1
	v_mul_f32_e32 v3, 0x4f7ffffe, v4
	v_cvt_u32_f32_e32 v3, v3
	v_sub_u32_e32 v4, 0, v1
	v_mul_lo_u32 v4, v4, v3
	v_mul_hi_u32 v4, v3, v4
	v_add_u32_e32 v3, v3, v4
	v_mul_hi_u32 v3, v2, v3
	v_mul_lo_u32 v4, v3, v1
	v_sub_u32_e32 v2, v2, v4
	v_add_u32_e32 v6, 1, v3
	v_cmp_ge_u32_e32 vcc, v2, v1
	v_sub_u32_e32 v4, v2, v1
	s_nop 0
	v_cndmask_b32_e32 v3, v3, v6, vcc
	v_cndmask_b32_e32 v2, v2, v4, vcc
	v_add_u32_e32 v4, 1, v3
	v_cmp_ge_u32_e32 vcc, v2, v1
	s_nop 1
	v_cndmask_b32_e32 v4, v3, v4, vcc
	v_mul_lo_u32 v2, v1, v4
	v_add_u32_e32 v1, v2, v1
	v_cmp_eq_u32_e32 vcc, v1, v1
	v_mov_b64_e32 v[2:3], s[10:11]
	s_and_saveexec_b64 s[8:9], vcc
	s_cbranch_execz .LBB0_174
	v_mov_b32_e32 v1, 0
	global_load_dword v2, v1, s[10:11] sc1
	s_mov_b64 s[16:17], 0
	s_waitcnt vmcnt(0)
	v_cmp_lt_u32_e32 vcc, v2, v255
	s_and_saveexec_b64 s[14:15], vcc
	s_cbranch_execz .LBB0_173
	s_add_u32 s12, s6, 0xc0200
	s_addc_u32 s13, s7, 0
	s_mov_b32 s24, 1
	s_mov_b64 s[6:7], 0
	s_branch .LBB0_166

; __device__ __forceinline__ unsigned xb_ld(unsigned* p)              { return __hip_atomic_load(p, __ATOMIC_RELAXED, __HIP_MEMORY_SCOPE_AGENT); }
; #define XB_SPIN(cond, bar) do { unsigned _sp = 0; while (cond) { __builtin_amdgcn_s_sleep(1); \
;     if ((++_sp & 255u) == 0u) { if (xb_ld(&(bar)[XB_TMO])) break; if (_sp > XB_SPIN_CAP) { atomicAdd(&(bar)[XB_TMO], 1u); break; } } } } while (0)
; __device__ __forceinline__ void xcd_barrier(const XcdBarrier& b) {
;     ...
;             else XB_SPIN(xb_ld(&bar[XB_TOPGEN]) == tg, bar);
.LBB0_168:
	global_load_dword v2, v1, s[10:11] sc1
	s_add_i32 s24, s24, 1
	s_mov_b64 s[18:19], -1
	s_waitcnt vmcnt(0)
	v_cmp_ge_u32_e32 vcc, v2, v255
	s_orn2_b64 s[22:23], vcc, exec
	s_branch .LBB0_165

; __device__ __forceinline__ unsigned xb_ld(unsigned* p)              { return __hip_atomic_load(p, __ATOMIC_RELAXED, __HIP_MEMORY_SCOPE_AGENT); }
; __device__ __forceinline__ unsigned xb_add(unsigned* p, unsigned v) { return __hip_atomic_fetch_add(p, v, __ATOMIC_RELAXED, __HIP_MEMORY_SCOPE_AGENT); }
; #define XB_SPIN(cond, bar) do { unsigned _sp = 0; while (cond) { __builtin_amdgcn_s_sleep(1); \
;     if ((++_sp & 255u) == 0u) { if (xb_ld(&(bar)[XB_TMO])) break; if (_sp > XB_SPIN_CAP) { atomicAdd(&(bar)[XB_TMO], 1u); break; } } } } while (0)
; __device__ __forceinline__ void xcd_barrier(const XcdBarrier& b) {
;     ...
;             const unsigned og = xb_add(&bar[XB_TOP], 1u);
;             const unsigned tg = og / nx;
;             if (og + 1u == (tg + 1u) * nx) xb_add(&bar[XB_TOPGEN], 1u);
;             else XB_SPIN(xb_ld(&bar[XB_TOPGEN]) == tg, bar);
;             __builtin_amdgcn_fence(__ATOMIC_ACQUIRE, "agent");
;             xb_add(&bar[XB_XGEN(b.x)], 1u);
;             asm volatile("s_waitcnt vmcnt(0)" ::: "memory");
.LBB0_174:
	s_or_b64 exec, exec, s[8:9]
	s_and_saveexec_b64 s[6:7], s[12:13]
	s_cbranch_execz .LBB0_176
	v_mov_b32_e32 v1, 1
	global_atomic_add v[2:3], v1, off
.LBB0_176:
	s_or_b64 exec, exec, s[6:7]
	s_mov_b64 s[6:7], exec
	v_mbcnt_lo_u32_b32 v1, s6, 0
	v_mbcnt_hi_u32_b32 v1, s7, v1
	s_mov_b32 s11, 0
	v_cmp_eq_u32_e32 vcc, 0, v1
	s_waitcnt vmcnt(0)
	s_and_saveexec_b64 s[8:9], vcc
	s_cbranch_execz .LBB0_178
	s_add_i32 s10, s28, 0x900
	s_lshl_b64 s[10:11], s[10:11], 2
	s_add_u32 s10, s26, s10
	s_addc_u32 s11, s27, s11
	s_bcnt1_i32_b64 s6, s[6:7]
	v_mov_b32_e32 v1, 0
	v_mov_b32_e32 v2, s6

; __device__ __forceinline__ unsigned xb_ld(unsigned* p)              { return __hip_atomic_load(p, __ATOMIC_RELAXED, __HIP_MEMORY_SCOPE_AGENT); }
; __device__ __forceinline__ unsigned xb_add(unsigned* p, unsigned v) { return __hip_atomic_fetch_add(p, v, __ATOMIC_RELAXED, __HIP_MEMORY_SCOPE_AGENT); }
; #define XB_SPIN(cond, bar) do { unsigned _sp = 0; while (cond) { __builtin_amdgcn_s_sleep(1); \
;     if ((++_sp & 255u) == 0u) { if (xb_ld(&(bar)[XB_TMO])) break; if (_sp > XB_SPIN_CAP) { atomicAdd(&(bar)[XB_TMO], 1u); break; } } } } while (0)
; __device__ __forceinline__ void xcd_barrier(const XcdBarrier& b) {
;     ...
;         const unsigned old = xb_add(&bar[XB_XSUB(b.x)], 1u);
;         const unsigned gen = old / nloc;
;         if (old + 1u == (gen + 1u) * nloc) {
;             __builtin_amdgcn_fence(__ATOMIC_RELEASE, "agent");
;             asm volatile("s_waitcnt vmcnt(0)" ::: "memory");
;             const unsigned og = xb_add(&bar[XB_TOP], 1u);
;             const unsigned tg = og / nx;
;             if (og + 1u == (tg + 1u) * nx) xb_add(&bar[XB_TOPGEN], 1u);
;             else XB_SPIN(xb_ld(&bar[XB_TOPGEN]) == tg, bar);
;             __builtin_amdgcn_fence(__ATOMIC_ACQUIRE, "agent");
;             xb_add(&bar[XB_XGEN(b.x)], 1u);
;             asm volatile("s_waitcnt vmcnt(0)" ::: "memory");
;         } else {
;             XB_SPIN(xb_ld(&bar[XB_XGEN(b.x)]) == gen, bar);
.LBB0_255:
	s_or_b64 exec, exec, s[10:11]
	v_cvt_f32_u32_e32 v6, v4
	s_waitcnt vmcnt(0)
	v_readfirstlane_b32 s8, v5
	v_sub_u32_e32 v5, 0, v4
	v_rcp_iflag_f32_e32 v6, v6
	v_add_u32_e32 v7, s8, v3
	v_mul_f32_e32 v6, 0x4f7ffffe, v6
	v_cvt_u32_f32_e32 v6, v6
	v_mul_lo_u32 v3, v5, v6
	v_mul_hi_u32 v3, v6, v3
	v_add_u32_e32 v3, v6, v3
	v_mul_hi_u32 v3, v7, v3
	v_mul_lo_u32 v5, v3, v4
	v_sub_u32_e32 v5, v7, v5
	v_add_u32_e32 v6, 1, v3
	v_cmp_ge_u32_e32 vcc, v5, v4
	s_nop 1
	v_cndmask_b32_e32 v3, v3, v6, vcc
	v_sub_u32_e32 v6, v5, v4
	v_cndmask_b32_e32 v5, v5, v6, vcc
	v_add_u32_e32 v6, 1, v3
	v_cmp_ge_u32_e32 vcc, v5, v4
	v_add_u32_e32 v5, 1, v7
	s_nop 0
	v_cndmask_b32_e32 v3, v3, v6, vcc
	v_mul_lo_u32 v6, v4, v3
	v_add_u32_e32 v4, v6, v4
	v_mad_u32_u24 v255, v3, v2, v2
	v_cmp_ne_u32_e32 vcc, v5, v4
	s_and_saveexec_b64 s[8:9], vcc
	s_xor_b64 s[8:9], exec, s[8:9]
	s_cbranch_execz .LBB0_269
	buffer_inv sc1
	s_add_i32 s10, s28, 0x900
	s_mov_b32 s11, 0
	s_lshl_b64 s[10:11], s[10:11], 2
	s_add_u32 s14, s26, s10
	s_addc_u32 s15, s27, s11
	s_waitcnt lgkmcnt(0)
	v_mov_b32_e32 v2, 0
	global_load_dword v4, v2, s[14:15] sc1
	s_waitcnt vmcnt(0)
	v_cmp_lt_u32_e32 vcc, v4, v255
	s_and_saveexec_b64 s[10:11], vcc
	s_cbranch_execz .LBB0_268
	s_add_u32 s12, s6, 0xc0200
	s_addc_u32 s13, s7, 0
	s_mov_b32 s29, 1
	s_mov_b64 s[16:17], 0
	s_branch .LBB0_259

; __device__ __forceinline__ unsigned xb_ld(unsigned* p)              { return __hip_atomic_load(p, __ATOMIC_RELAXED, __HIP_MEMORY_SCOPE_AGENT); }
; #define XB_SPIN(cond, bar) do { unsigned _sp = 0; while (cond) { __builtin_amdgcn_s_sleep(1); \
;     if ((++_sp & 255u) == 0u) { if (xb_ld(&(bar)[XB_TMO])) break; if (_sp > XB_SPIN_CAP) { atomicAdd(&(bar)[XB_TMO], 1u); break; } } } } while (0)
; __device__ __forceinline__ void xcd_barrier(const XcdBarrier& b) {
;     ...
;             XB_SPIN(xb_ld(&bar[XB_XGEN(b.x)]) == gen, bar);
.LBB0_261:
	global_load_dword v4, v2, s[14:15] sc1
	s_add_i32 s29, s29, 1
	s_mov_b64 s[22:23], -1
	s_waitcnt vmcnt(0)
	v_cmp_ge_u32_e32 vcc, v4, v255
	s_orn2_b64 s[20:21], vcc, exec
	s_branch .LBB0_258

; __device__ __forceinline__ unsigned xb_ld(unsigned* p)              { return __hip_atomic_load(p, __ATOMIC_RELAXED, __HIP_MEMORY_SCOPE_AGENT); }
; __device__ __forceinline__ unsigned xb_add(unsigned* p, unsigned v) { return __hip_atomic_fetch_add(p, v, __ATOMIC_RELAXED, __HIP_MEMORY_SCOPE_AGENT); }
; #define XB_SPIN(cond, bar) do { unsigned _sp = 0; while (cond) { __builtin_amdgcn_s_sleep(1); \
;     if ((++_sp & 255u) == 0u) { if (xb_ld(&(bar)[XB_TMO])) break; if (_sp > XB_SPIN_CAP) { atomicAdd(&(bar)[XB_TMO], 1u); break; } } } } while (0)
; __device__ __forceinline__ void xcd_barrier(const XcdBarrier& b) {
;     ...
;         if (old + 1u == (gen + 1u) * nloc) {
;             __builtin_amdgcn_fence(__ATOMIC_RELEASE, "agent");
;             asm volatile("s_waitcnt vmcnt(0)" ::: "memory");
;             const unsigned og = xb_add(&bar[XB_TOP], 1u);
;             const unsigned tg = og / nx;
;             if (og + 1u == (tg + 1u) * nx) xb_add(&bar[XB_TOPGEN], 1u);
;             else XB_SPIN(xb_ld(&bar[XB_TOPGEN]) == tg, bar);
;             __builtin_amdgcn_fence(__ATOMIC_ACQUIRE, "agent");
.LBB0_269:
	s_andn2_saveexec_b64 s[8:9], s[8:9]
	s_cbranch_execz .LBB0_289
	s_mov_b64 s[8:9], exec
	buffer_wbl2 sc1
	buffer_inv sc1
	s_waitcnt lgkmcnt(0)
	s_waitcnt vmcnt(0)
	v_mbcnt_lo_u32_b32 v3, s8, 0
	v_mbcnt_hi_u32_b32 v3, s9, v3
	v_cmp_eq_u32_e32 vcc, 0, v3
	s_and_saveexec_b64 s[10:11], vcc
	s_cbranch_execz .LBB0_272
	s_bcnt1_i32_b64 s8, s[8:9]
	v_mov_b32_e32 v4, 0xc2400
	v_mov_b32_e32 v5, s8
	global_atomic_add v4, v5, s[6:7]
	global_atomic_add v4, v5, s[6:7] offset:256
	global_atomic_add v4, v5, s[6:7] offset:512
	global_atomic_add v4, v5, s[6:7] offset:768
	global_atomic_add v4, v5, s[6:7] offset:1024
	global_atomic_add v4, v5, s[6:7] offset:1280
	global_atomic_add v4, v5, s[6:7] offset:1536
	global_atomic_add v4, v5, s[6:7] offset:1792
	global_atomic_add v4, v5, s[6:7] offset:2048
	global_atomic_add v4, v5, s[6:7] offset:2304
	global_atomic_add v4, v5, s[6:7] offset:2560
	global_atomic_add v4, v5, s[6:7] offset:2816
	global_atomic_add v4, v5, s[6:7] offset:3072
	global_atomic_add v4, v5, s[6:7] offset:3328
	global_atomic_add v4, v5, s[6:7] offset:3584
	global_atomic_add v4, v5, s[6:7] offset:3840
.LBB0_272:
	s_or_b64 exec, exec, s[10:11]
	v_cvt_f32_u32_e32 v5, v2
	s_waitcnt vmcnt(0)
	v_readfirstlane_b32 s8, v4
	s_add_i32 s10, s28, 0x900
	s_mov_b32 s11, 0
	s_lshl_b64 s[10:11], s[10:11], 2
	s_add_u32 s10, s26, s10
	s_addc_u32 s11, s27, s11
	v_rcp_iflag_f32_e32 v5, v5
	v_add_u32_e32 v3, s8, v3
	v_add_u32_e32 v6, 1, v3
	s_mov_b64 s[12:13], -1
	v_mul_f32_e32 v4, 0x4f7ffffe, v5
	v_cvt_u32_f32_e32 v4, v4
	v_sub_u32_e32 v5, 0, v2
	v_mul_lo_u32 v5, v5, v4
	v_mul_hi_u32 v5, v4, v5
	v_add_u32_e32 v4, v4, v5
	v_mul_hi_u32 v4, v3, v4
	v_mul_lo_u32 v5, v4, v2
	v_sub_u32_e32 v3, v3, v5
	v_add_u32_e32 v7, 1, v4
	v_cmp_ge_u32_e32 vcc, v3, v2
	v_sub_u32_e32 v5, v3, v2
	s_nop 0
	v_cndmask_b32_e32 v4, v4, v7, vcc
	v_cndmask_b32_e32 v3, v3, v5, vcc
	v_add_u32_e32 v5, 1, v4
	v_cmp_ge_u32_e32 vcc, v3, v2
	s_nop 1
	v_cndmask_b32_e32 v4, v4, v5, vcc
	v_mul_lo_u32 v3, v2, v4
	v_add_u32_e32 v2, v3, v2
	v_cmp_eq_u32_e32 vcc, v2, v2
	v_mov_b64_e32 v[2:3], s[10:11]
	s_and_saveexec_b64 s[8:9], vcc
	s_cbranch_execz .LBB0_284
	v_mov_b32_e32 v2, 0
	global_load_dword v3, v2, s[10:11] sc1
	s_mov_b64 s[16:17], 0
	s_waitcnt vmcnt(0)
	v_cmp_lt_u32_e32 vcc, v3, v255
	s_and_saveexec_b64 s[14:15], vcc
	s_cbranch_execz .LBB0_283
	s_add_u32 s12, s6, 0xc0200
	s_addc_u32 s13, s7, 0
	s_mov_b32 s24, 1
	s_mov_b64 s[6:7], 0
	s_branch .LBB0_276

; __device__ __forceinline__ unsigned xb_ld(unsigned* p)              { return __hip_atomic_load(p, __ATOMIC_RELAXED, __HIP_MEMORY_SCOPE_AGENT); }
; #define XB_SPIN(cond, bar) do { unsigned _sp = 0; while (cond) { __builtin_amdgcn_s_sleep(1); \
;     if ((++_sp & 255u) == 0u) { if (xb_ld(&(bar)[XB_TMO])) break; if (_sp > XB_SPIN_CAP) { atomicAdd(&(bar)[XB_TMO], 1u); break; } } } } while (0)
; __device__ __forceinline__ void xcd_barrier(const XcdBarrier& b) {
;     ...
;             else XB_SPIN(xb_ld(&bar[XB_TOPGEN]) == tg, bar);
.LBB0_278:
	global_load_dword v3, v2, s[10:11] sc1
	s_add_i32 s24, s24, 1
	s_mov_b64 s[18:19], -1
	s_waitcnt vmcnt(0)
	v_cmp_ge_u32_e32 vcc, v3, v255
	s_orn2_b64 s[22:23], vcc, exec
	s_branch .LBB0_275

; __device__ __forceinline__ unsigned xb_ld(unsigned* p)              { return __hip_atomic_load(p, __ATOMIC_RELAXED, __HIP_MEMORY_SCOPE_AGENT); }
; __device__ __forceinline__ unsigned xb_add(unsigned* p, unsigned v) { return __hip_atomic_fetch_add(p, v, __ATOMIC_RELAXED, __HIP_MEMORY_SCOPE_AGENT); }
; #define XB_SPIN(cond, bar) do { unsigned _sp = 0; while (cond) { __builtin_amdgcn_s_sleep(1); \
;     if ((++_sp & 255u) == 0u) { if (xb_ld(&(bar)[XB_TMO])) break; if (_sp > XB_SPIN_CAP) { atomicAdd(&(bar)[XB_TMO], 1u); break; } } } } while (0)
; __device__ __forceinline__ void xcd_barrier(const XcdBarrier& b) {
;     ...
;             const unsigned og = xb_add(&bar[XB_TOP], 1u);
;             const unsigned tg = og / nx;
;             if (og + 1u == (tg + 1u) * nx) xb_add(&bar[XB_TOPGEN], 1u);
;             else XB_SPIN(xb_ld(&bar[XB_TOPGEN]) == tg, bar);
;             __builtin_amdgcn_fence(__ATOMIC_ACQUIRE, "agent");
;             xb_add(&bar[XB_XGEN(b.x)], 1u);
;             asm volatile("s_waitcnt vmcnt(0)" ::: "memory");
.LBB0_284:
	s_or_b64 exec, exec, s[8:9]
	s_and_saveexec_b64 s[6:7], s[12:13]
	s_cbranch_execz .LBB0_286
	v_mov_b32_e32 v4, 1
	global_atomic_add v[2:3], v4, off
.LBB0_286:
	s_or_b64 exec, exec, s[6:7]
	s_mov_b64 s[6:7], exec
	v_mbcnt_lo_u32_b32 v2, s6, 0
	v_mbcnt_hi_u32_b32 v2, s7, v2
	s_mov_b32 s11, 0
	v_cmp_eq_u32_e32 vcc, 0, v2
	s_waitcnt vmcnt(0)
	s_and_saveexec_b64 s[8:9], vcc
	s_cbranch_execz .LBB0_288
	s_add_i32 s10, s28, 0x900
	s_lshl_b64 s[10:11], s[10:11], 2
	s_add_u32 s10, s26, s10
	s_addc_u32 s11, s27, s11
	s_bcnt1_i32_b64 s6, s[6:7]
	v_mov_b32_e32 v2, 0
	v_mov_b32_e32 v3, s6

; __device__ __forceinline__ unsigned xb_ld(unsigned* p)              { return __hip_atomic_load(p, __ATOMIC_RELAXED, __HIP_MEMORY_SCOPE_AGENT); }
; __device__ __forceinline__ unsigned xb_add(unsigned* p, unsigned v) { return __hip_atomic_fetch_add(p, v, __ATOMIC_RELAXED, __HIP_MEMORY_SCOPE_AGENT); }
; #define XB_SPIN(cond, bar) do { unsigned _sp = 0; while (cond) { __builtin_amdgcn_s_sleep(1); \
;     if ((++_sp & 255u) == 0u) { if (xb_ld(&(bar)[XB_TMO])) break; if (_sp > XB_SPIN_CAP) { atomicAdd(&(bar)[XB_TMO], 1u); break; } } } } while (0)
; __device__ __forceinline__ void xcd_barrier(const XcdBarrier& b) {
;     ...
;             const unsigned og = xb_add(&bar[XB_TOP], 1u);
;             const unsigned tg = og / nx;
;             if (og + 1u == (tg + 1u) * nx) xb_add(&bar[XB_TOPGEN], 1u);
;             else XB_SPIN(xb_ld(&bar[XB_TOPGEN]) == tg, bar);
;             __builtin_amdgcn_fence(__ATOMIC_ACQUIRE, "agent");
;             xb_add(&bar[XB_XGEN(b.x)], 1u);
;             asm volatile("s_waitcnt vmcnt(0)" ::: "memory");
.LBB0_383:
	s_or_b64 exec, exec, s[8:9]
	s_and_saveexec_b64 s[6:7], s[12:13]
	s_cbranch_execz .LBB0_385
	v_mov_b32_e32 v4, 1
	global_atomic_add v[2:3], v4, off
.LBB0_385:
	s_or_b64 exec, exec, s[6:7]
	s_mov_b64 s[6:7], exec
	v_mbcnt_lo_u32_b32 v2, s6, 0
	v_mbcnt_hi_u32_b32 v2, s7, v2
	s_mov_b32 s11, 0
	v_cmp_eq_u32_e32 vcc, 0, v2
	s_waitcnt vmcnt(0)
	s_and_saveexec_b64 s[8:9], vcc
	s_cbranch_execz .LBB0_387
	s_add_i32 s10, s28, 0x900
	s_lshl_b64 s[10:11], s[10:11], 2
	s_add_u32 s10, s26, s10
	s_addc_u32 s11, s27, s11
	s_bcnt1_i32_b64 s6, s[6:7]
	v_mov_b32_e32 v2, 0
	v_mov_b32_e32 v3, s6

; __device__ __forceinline__ unsigned xb_ld(unsigned* p)              { return __hip_atomic_load(p, __ATOMIC_RELAXED, __HIP_MEMORY_SCOPE_AGENT); }
; __device__ __forceinline__ unsigned xb_add(unsigned* p, unsigned v) { return __hip_atomic_fetch_add(p, v, __ATOMIC_RELAXED, __HIP_MEMORY_SCOPE_AGENT); }
; #define XB_SPIN(cond, bar) do { unsigned _sp = 0; while (cond) { __builtin_amdgcn_s_sleep(1); \
;     if ((++_sp & 255u) == 0u) { if (xb_ld(&(bar)[XB_TMO])) break; if (_sp > XB_SPIN_CAP) { atomicAdd(&(bar)[XB_TMO], 1u); break; } } } } while (0)
; __device__ __forceinline__ void xcd_barrier(const XcdBarrier& b) {
;     ...
;             const unsigned og = xb_add(&bar[XB_TOP], 1u);
;             const unsigned tg = og / nx;
;             if (og + 1u == (tg + 1u) * nx) xb_add(&bar[XB_TOPGEN], 1u);
;             else XB_SPIN(xb_ld(&bar[XB_TOPGEN]) == tg, bar);
;             __builtin_amdgcn_fence(__ATOMIC_ACQUIRE, "agent");
;             xb_add(&bar[XB_XGEN(b.x)], 1u);
;             asm volatile("s_waitcnt vmcnt(0)" ::: "memory");
.LBB0_664:
	s_or_b64 exec, exec, s[8:9]
	s_and_saveexec_b64 s[6:7], s[12:13]
	s_cbranch_execz .LBB0_666
	v_mov_b32_e32 v4, 1
	global_atomic_add v[2:3], v4, off
.LBB0_666:
	s_or_b64 exec, exec, s[6:7]
	s_mov_b64 s[6:7], exec
	v_mbcnt_lo_u32_b32 v2, s6, 0
	v_mbcnt_hi_u32_b32 v2, s7, v2
	s_mov_b32 s11, 0
	v_cmp_eq_u32_e32 vcc, 0, v2
	s_waitcnt vmcnt(0)
	s_and_saveexec_b64 s[8:9], vcc
	s_cbranch_execz .LBB0_668
	s_add_i32 s10, s28, 0x900
	s_lshl_b64 s[10:11], s[10:11], 2
	s_add_u32 s10, s26, s10
	s_addc_u32 s11, s27, s11
	s_bcnt1_i32_b64 s6, s[6:7]
	v_mov_b32_e32 v2, 0
	v_mov_b32_e32 v3, s6

; __device__ __forceinline__ unsigned xb_ld(unsigned* p)              { return __hip_atomic_load(p, __ATOMIC_RELAXED, __HIP_MEMORY_SCOPE_AGENT); }
; __device__ __forceinline__ unsigned xb_add(unsigned* p, unsigned v) { return __hip_atomic_fetch_add(p, v, __ATOMIC_RELAXED, __HIP_MEMORY_SCOPE_AGENT); }
; #define XB_SPIN(cond, bar) do { unsigned _sp = 0; while (cond) { __builtin_amdgcn_s_sleep(1); \
;     if ((++_sp & 255u) == 0u) { if (xb_ld(&(bar)[XB_TMO])) break; if (_sp > XB_SPIN_CAP) { atomicAdd(&(bar)[XB_TMO], 1u); break; } } } } while (0)
; __device__ __forceinline__ void xcd_barrier(const XcdBarrier& b) {
;     ...
;             const unsigned og = xb_add(&bar[XB_TOP], 1u);
;             const unsigned tg = og / nx;
;             if (og + 1u == (tg + 1u) * nx) xb_add(&bar[XB_TOPGEN], 1u);
;             else XB_SPIN(xb_ld(&bar[XB_TOPGEN]) == tg, bar);
;             __builtin_amdgcn_fence(__ATOMIC_ACQUIRE, "agent");
;             xb_add(&bar[XB_XGEN(b.x)], 1u);
;             asm volatile("s_waitcnt vmcnt(0)" ::: "memory");
.LBB0_1325:
	s_or_b64 exec, exec, s[8:9]
	s_and_saveexec_b64 s[6:7], s[12:13]
	s_cbranch_execz .LBB0_1327
	v_mov_b32_e32 v4, 1
	global_atomic_add v[2:3], v4, off
.LBB0_1327:
	s_or_b64 exec, exec, s[6:7]
	s_mov_b64 s[6:7], exec
	v_mbcnt_lo_u32_b32 v2, s6, 0
	v_mbcnt_hi_u32_b32 v2, s7, v2
	s_mov_b32 s11, 0
	v_cmp_eq_u32_e32 vcc, 0, v2
	s_waitcnt vmcnt(0)
	s_and_saveexec_b64 s[8:9], vcc
	s_cbranch_execz .LBB0_1329
	s_add_i32 s10, s28, 0x900
	s_lshl_b64 s[10:11], s[10:11], 2
	s_add_u32 s10, s26, s10
	s_addc_u32 s11, s27, s11
	s_bcnt1_i32_b64 s6, s[6:7]
	v_mov_b32_e32 v2, 0
	v_mov_b32_e32 v3, s6

; __device__ __forceinline__ unsigned xb_ld(unsigned* p)              { return __hip_atomic_load(p, __ATOMIC_RELAXED, __HIP_MEMORY_SCOPE_AGENT); }
; __device__ __forceinline__ unsigned xb_add(unsigned* p, unsigned v) { return __hip_atomic_fetch_add(p, v, __ATOMIC_RELAXED, __HIP_MEMORY_SCOPE_AGENT); }
; #define XB_SPIN(cond, bar) do { unsigned _sp = 0; while (cond) { __builtin_amdgcn_s_sleep(1); \
;     if ((++_sp & 255u) == 0u) { if (xb_ld(&(bar)[XB_TMO])) break; if (_sp > XB_SPIN_CAP) { atomicAdd(&(bar)[XB_TMO], 1u); break; } } } } while (0)
; __device__ __forceinline__ void xcd_barrier(const XcdBarrier& b) {
;     ...
;             const unsigned og = xb_add(&bar[XB_TOP], 1u);
;             const unsigned tg = og / nx;
;             if (og + 1u == (tg + 1u) * nx) xb_add(&bar[XB_TOPGEN], 1u);
;             else XB_SPIN(xb_ld(&bar[XB_TOPGEN]) == tg, bar);
;             __builtin_amdgcn_fence(__ATOMIC_ACQUIRE, "agent");
;             xb_add(&bar[XB_XGEN(b.x)], 1u);
;             asm volatile("s_waitcnt vmcnt(0)" ::: "memory");
.LBB0_1480:
	s_or_b64 exec, exec, s[8:9]
	s_and_saveexec_b64 s[6:7], s[12:13]
	s_cbranch_execz .LBB0_1482
	v_mov_b32_e32 v4, 1
	global_atomic_add v[2:3], v4, off
.LBB0_1482:
	s_or_b64 exec, exec, s[6:7]
	s_mov_b64 s[6:7], exec
	v_mbcnt_lo_u32_b32 v2, s6, 0
	v_mbcnt_hi_u32_b32 v2, s7, v2
	s_mov_b32 s11, 0
	v_cmp_eq_u32_e32 vcc, 0, v2
	s_waitcnt vmcnt(0)
	s_and_saveexec_b64 s[8:9], vcc
	s_cbranch_execz .LBB0_1484
	s_add_i32 s10, s28, 0x900
	s_lshl_b64 s[10:11], s[10:11], 2
	s_add_u32 s10, s26, s10
	s_addc_u32 s11, s27, s11
	s_bcnt1_i32_b64 s6, s[6:7]
	v_mov_b32_e32 v2, 0
	v_mov_b32_e32 v3, s6

; __device__ __forceinline__ unsigned xb_ld(unsigned* p)              { return __hip_atomic_load(p, __ATOMIC_RELAXED, __HIP_MEMORY_SCOPE_AGENT); }
; __device__ __forceinline__ unsigned xb_add(unsigned* p, unsigned v) { return __hip_atomic_fetch_add(p, v, __ATOMIC_RELAXED, __HIP_MEMORY_SCOPE_AGENT); }
; #define XB_SPIN(cond, bar) do { unsigned _sp = 0; while (cond) { __builtin_amdgcn_s_sleep(1); \
;     if ((++_sp & 255u) == 0u) { if (xb_ld(&(bar)[XB_TMO])) break; if (_sp > XB_SPIN_CAP) { atomicAdd(&(bar)[XB_TMO], 1u); break; } } } } while (0)
; __device__ __forceinline__ void xcd_barrier(const XcdBarrier& b) {
;     ...
;             const unsigned og = xb_add(&bar[XB_TOP], 1u);
;             const unsigned tg = og / nx;
;             if (og + 1u == (tg + 1u) * nx) xb_add(&bar[XB_TOPGEN], 1u);
;             else XB_SPIN(xb_ld(&bar[XB_TOPGEN]) == tg, bar);
;             __builtin_amdgcn_fence(__ATOMIC_ACQUIRE, "agent");
;             xb_add(&bar[XB_XGEN(b.x)], 1u);
;             asm volatile("s_waitcnt vmcnt(0)" ::: "memory");
.LBB0_1536:
	s_or_b64 exec, exec, s[8:9]
	s_and_saveexec_b64 s[6:7], s[12:13]
	s_cbranch_execz .LBB0_1538
	v_mov_b32_e32 v4, 1
	global_atomic_add v[2:3], v4, off
.LBB0_1538:
	s_or_b64 exec, exec, s[6:7]
	s_mov_b64 s[6:7], exec
	v_mbcnt_lo_u32_b32 v2, s6, 0
	v_mbcnt_hi_u32_b32 v2, s7, v2
	s_mov_b32 s11, 0
	v_cmp_eq_u32_e32 vcc, 0, v2
	s_waitcnt vmcnt(0)
	s_and_saveexec_b64 s[8:9], vcc
	s_cbranch_execz .LBB0_1540
	s_add_i32 s10, s28, 0x900
	s_lshl_b64 s[10:11], s[10:11], 2
	s_add_u32 s10, s26, s10
	s_addc_u32 s11, s27, s11
	s_bcnt1_i32_b64 s6, s[6:7]
	v_mov_b32_e32 v2, 0
	v_mov_b32_e32 v3, s6

; __device__ __forceinline__ unsigned xb_ld(unsigned* p)              { return __hip_atomic_load(p, __ATOMIC_RELAXED, __HIP_MEMORY_SCOPE_AGENT); }
; __device__ __forceinline__ unsigned xb_add(unsigned* p, unsigned v) { return __hip_atomic_fetch_add(p, v, __ATOMIC_RELAXED, __HIP_MEMORY_SCOPE_AGENT); }
; #define XB_SPIN(cond, bar) do { unsigned _sp = 0; while (cond) { __builtin_amdgcn_s_sleep(1); \
;     if ((++_sp & 255u) == 0u) { if (xb_ld(&(bar)[XB_TMO])) break; if (_sp > XB_SPIN_CAP) { atomicAdd(&(bar)[XB_TMO], 1u); break; } } } } while (0)
; __device__ __forceinline__ void xcd_barrier(const XcdBarrier& b) {
;     ...
;         const unsigned old = xb_add(&bar[XB_XSUB(b.x)], 1u);
;         const unsigned gen = old / nloc;
;         if (old + 1u == (gen + 1u) * nloc) {
;             __builtin_amdgcn_fence(__ATOMIC_RELEASE, "agent");
;             asm volatile("s_waitcnt vmcnt(0)" ::: "memory");
;             const unsigned og = xb_add(&bar[XB_TOP], 1u);
;             const unsigned tg = og / nx;
;             if (og + 1u == (tg + 1u) * nx) xb_add(&bar[XB_TOPGEN], 1u);
;             else XB_SPIN(xb_ld(&bar[XB_TOPGEN]) == tg, bar);
;             __builtin_amdgcn_fence(__ATOMIC_ACQUIRE, "agent");
;             xb_add(&bar[XB_XGEN(b.x)], 1u);
;             asm volatile("s_waitcnt vmcnt(0)" ::: "memory");
;         } else {
;             XB_SPIN(xb_ld(&bar[XB_XGEN(b.x)]) == gen, bar);
.LBB0_1619:
	s_or_b64 exec, exec, s[16:17]
	v_cvt_f32_u32_e32 v6, v4
	s_waitcnt vmcnt(0)
	v_readfirstlane_b32 s10, v5
	v_sub_u32_e32 v5, 0, v4
	v_rcp_iflag_f32_e32 v6, v6
	v_add_u32_e32 v7, s10, v3
	v_mul_f32_e32 v6, 0x4f7ffffe, v6
	v_cvt_u32_f32_e32 v6, v6
	v_mul_lo_u32 v3, v5, v6
	v_mul_hi_u32 v3, v6, v3
	v_add_u32_e32 v3, v6, v3
	v_mul_hi_u32 v3, v7, v3
	v_mul_lo_u32 v5, v3, v4
	v_sub_u32_e32 v5, v7, v5
	v_add_u32_e32 v6, 1, v3
	v_cmp_ge_u32_e32 vcc, v5, v4
	s_nop 1
	v_cndmask_b32_e32 v3, v3, v6, vcc
	v_sub_u32_e32 v6, v5, v4
	v_cndmask_b32_e32 v5, v5, v6, vcc
	v_add_u32_e32 v6, 1, v3
	v_cmp_ge_u32_e32 vcc, v5, v4
	v_add_u32_e32 v5, 1, v7
	s_nop 0
	v_cndmask_b32_e32 v3, v3, v6, vcc
	v_mul_lo_u32 v6, v4, v3
	v_add_u32_e32 v4, v6, v4
	v_mad_u32_u24 v255, v3, v2, v2
	v_cmp_ne_u32_e32 vcc, v5, v4
	s_and_saveexec_b64 s[10:11], vcc
	s_xor_b64 s[10:11], exec, s[10:11]
	s_cbranch_execz .LBB0_1633
	buffer_inv sc1
	s_add_i32 s16, s36, 0x900
	s_mov_b32 s17, 0
	s_lshl_b64 s[16:17], s[16:17], 2
	s_add_u32 s20, s34, s16
	s_addc_u32 s21, s35, s17
	s_waitcnt lgkmcnt(0)
	v_mov_b32_e32 v2, 0
	global_load_dword v4, v2, s[20:21] sc1
	s_waitcnt vmcnt(0)
	v_cmp_lt_u32_e32 vcc, v4, v255
	s_and_saveexec_b64 s[16:17], vcc
	s_cbranch_execz .LBB0_1632
	s_add_u32 s18, s8, 0xc0200
	s_addc_u32 s19, s9, 0
	s_mov_b32 s37, 1
	s_mov_b64 s[22:23], 0
	s_branch .LBB0_1623

; __device__ __forceinline__ unsigned xb_ld(unsigned* p)              { return __hip_atomic_load(p, __ATOMIC_RELAXED, __HIP_MEMORY_SCOPE_AGENT); }
; #define XB_SPIN(cond, bar) do { unsigned _sp = 0; while (cond) { __builtin_amdgcn_s_sleep(1); \
;     if ((++_sp & 255u) == 0u) { if (xb_ld(&(bar)[XB_TMO])) break; if (_sp > XB_SPIN_CAP) { atomicAdd(&(bar)[XB_TMO], 1u); break; } } } } while (0)
; __device__ __forceinline__ void xcd_barrier(const XcdBarrier& b) {
;     ...
;             XB_SPIN(xb_ld(&bar[XB_XGEN(b.x)]) == gen, bar);
.LBB0_1625:
	global_load_dword v4, v2, s[20:21] sc1
	s_add_i32 s37, s37, 1
	s_mov_b64 s[28:29], -1
	s_waitcnt vmcnt(0)
	v_cmp_ge_u32_e32 vcc, v4, v255
	s_orn2_b64 s[26:27], vcc, exec
	s_branch .LBB0_1622

; __device__ __forceinline__ unsigned xb_ld(unsigned* p)              { return __hip_atomic_load(p, __ATOMIC_RELAXED, __HIP_MEMORY_SCOPE_AGENT); }
; __device__ __forceinline__ unsigned xb_add(unsigned* p, unsigned v) { return __hip_atomic_fetch_add(p, v, __ATOMIC_RELAXED, __HIP_MEMORY_SCOPE_AGENT); }
; #define XB_SPIN(cond, bar) do { unsigned _sp = 0; while (cond) { __builtin_amdgcn_s_sleep(1); \
;     if ((++_sp & 255u) == 0u) { if (xb_ld(&(bar)[XB_TMO])) break; if (_sp > XB_SPIN_CAP) { atomicAdd(&(bar)[XB_TMO], 1u); break; } } } } while (0)
; __device__ __forceinline__ void xcd_barrier(const XcdBarrier& b) {
;     ...
;         const unsigned old = xb_add(&bar[XB_XSUB(b.x)], 1u);
;         const unsigned gen = old / nloc;
;         if (old + 1u == (gen + 1u) * nloc) {
;             __builtin_amdgcn_fence(__ATOMIC_RELEASE, "agent");
;             asm volatile("s_waitcnt vmcnt(0)" ::: "memory");
;             const unsigned og = xb_add(&bar[XB_TOP], 1u);
;             const unsigned tg = og / nx;
;             if (og + 1u == (tg + 1u) * nx) xb_add(&bar[XB_TOPGEN], 1u);
;             else XB_SPIN(xb_ld(&bar[XB_TOPGEN]) == tg, bar);
;             __builtin_amdgcn_fence(__ATOMIC_ACQUIRE, "agent");
;             xb_add(&bar[XB_XGEN(b.x)], 1u);
;             asm volatile("s_waitcnt vmcnt(0)" ::: "memory");
.LBB0_1633:
	s_andn2_saveexec_b64 s[10:11], s[10:11]
	s_cbranch_execz .LBB0_1653
	s_mov_b64 s[10:11], exec
	buffer_wbl2 sc1
	buffer_inv sc1
	s_waitcnt lgkmcnt(0)
	s_waitcnt vmcnt(0)
	v_mbcnt_lo_u32_b32 v3, s10, 0
	v_mbcnt_hi_u32_b32 v3, s11, v3
	v_cmp_eq_u32_e32 vcc, 0, v3
	s_and_saveexec_b64 s[16:17], vcc
	s_cbranch_execz .LBB0_1636
	s_bcnt1_i32_b64 s10, s[10:11]
	v_mov_b32_e32 v4, 0xc2400
	v_mov_b32_e32 v5, s10
	global_atomic_add v4, v5, s[8:9]
	global_atomic_add v4, v5, s[8:9] offset:256
	global_atomic_add v4, v5, s[8:9] offset:512
	global_atomic_add v4, v5, s[8:9] offset:768
	global_atomic_add v4, v5, s[8:9] offset:1024
	global_atomic_add v4, v5, s[8:9] offset:1280
	global_atomic_add v4, v5, s[8:9] offset:1536
	global_atomic_add v4, v5, s[8:9] offset:1792
	global_atomic_add v4, v5, s[8:9] offset:2048
	global_atomic_add v4, v5, s[8:9] offset:2304
	global_atomic_add v4, v5, s[8:9] offset:2560
	global_atomic_add v4, v5, s[8:9] offset:2816
	global_atomic_add v4, v5, s[8:9] offset:3072
	global_atomic_add v4, v5, s[8:9] offset:3328
	global_atomic_add v4, v5, s[8:9] offset:3584
	global_atomic_add v4, v5, s[8:9] offset:3840
.LBB0_1636:
	s_or_b64 exec, exec, s[16:17]
	v_cvt_f32_u32_e32 v5, v2
	s_waitcnt vmcnt(0)
	v_readfirstlane_b32 s10, v4
	s_add_i32 s16, s36, 0x900
	s_mov_b32 s17, 0
	s_lshl_b64 s[16:17], s[16:17], 2
	s_add_u32 s16, s34, s16
	s_addc_u32 s17, s35, s17
	v_rcp_iflag_f32_e32 v5, v5
	v_add_u32_e32 v3, s10, v3
	v_add_u32_e32 v6, 1, v3
	s_mov_b64 s[18:19], -1
	v_mul_f32_e32 v4, 0x4f7ffffe, v5
	v_cvt_u32_f32_e32 v4, v4
	v_sub_u32_e32 v5, 0, v2
	v_mul_lo_u32 v5, v5, v4
	v_mul_hi_u32 v5, v4, v5
	v_add_u32_e32 v4, v4, v5
	v_mul_hi_u32 v4, v3, v4
	v_mul_lo_u32 v5, v4, v2
	v_sub_u32_e32 v3, v3, v5
	v_add_u32_e32 v7, 1, v4
	v_cmp_ge_u32_e32 vcc, v3, v2
	v_sub_u32_e32 v5, v3, v2
	s_nop 0
	v_cndmask_b32_e32 v4, v4, v7, vcc
	v_cndmask_b32_e32 v3, v3, v5, vcc
	v_add_u32_e32 v5, 1, v4
	v_cmp_ge_u32_e32 vcc, v3, v2
	s_nop 1
	v_cndmask_b32_e32 v4, v4, v5, vcc
	v_mul_lo_u32 v3, v2, v4
	v_add_u32_e32 v2, v3, v2
	v_cmp_eq_u32_e32 vcc, v2, v2
	v_mov_b64_e32 v[2:3], s[16:17]
	s_and_saveexec_b64 s[10:11], vcc
	s_cbranch_execz .LBB0_1648
	v_mov_b32_e32 v2, 0
	global_load_dword v3, v2, s[16:17] sc1
	s_mov_b64 s[22:23], 0
	s_waitcnt vmcnt(0)
	v_cmp_lt_u32_e32 vcc, v3, v255
	s_and_saveexec_b64 s[20:21], vcc
	s_cbranch_execz .LBB0_1647
	s_add_u32 s18, s8, 0xc0200
	s_addc_u32 s19, s9, 0
	s_mov_b32 s30, 1
	s_mov_b64 s[8:9], 0
	s_branch .LBB0_1640

; __device__ __forceinline__ unsigned xb_ld(unsigned* p)              { return __hip_atomic_load(p, __ATOMIC_RELAXED, __HIP_MEMORY_SCOPE_AGENT); }
; #define XB_SPIN(cond, bar) do { unsigned _sp = 0; while (cond) { __builtin_amdgcn_s_sleep(1); \
;     if ((++_sp & 255u) == 0u) { if (xb_ld(&(bar)[XB_TMO])) break; if (_sp > XB_SPIN_CAP) { atomicAdd(&(bar)[XB_TMO], 1u); break; } } } } while (0)
; __device__ __forceinline__ void xcd_barrier(const XcdBarrier& b) {
;     ...
;             else XB_SPIN(xb_ld(&bar[XB_TOPGEN]) == tg, bar);
.LBB0_1642:
	global_load_dword v3, v2, s[16:17] sc1
	s_add_i32 s30, s30, 1
	s_mov_b64 s[24:25], -1
	s_waitcnt vmcnt(0)
	v_cmp_ge_u32_e32 vcc, v3, v255
	s_orn2_b64 s[28:29], vcc, exec
	s_branch .LBB0_1639

; __device__ __forceinline__ unsigned xb_ld(unsigned* p)              { return __hip_atomic_load(p, __ATOMIC_RELAXED, __HIP_MEMORY_SCOPE_AGENT); }
; __device__ __forceinline__ unsigned xb_add(unsigned* p, unsigned v) { return __hip_atomic_fetch_add(p, v, __ATOMIC_RELAXED, __HIP_MEMORY_SCOPE_AGENT); }
; #define XB_SPIN(cond, bar) do { unsigned _sp = 0; while (cond) { __builtin_amdgcn_s_sleep(1); \
;     if ((++_sp & 255u) == 0u) { if (xb_ld(&(bar)[XB_TMO])) break; if (_sp > XB_SPIN_CAP) { atomicAdd(&(bar)[XB_TMO], 1u); break; } } } } while (0)
; __device__ __forceinline__ void xcd_barrier(const XcdBarrier& b) {
;     ...
;             const unsigned og = xb_add(&bar[XB_TOP], 1u);
;             const unsigned tg = og / nx;
;             if (og + 1u == (tg + 1u) * nx) xb_add(&bar[XB_TOPGEN], 1u);
;             else XB_SPIN(xb_ld(&bar[XB_TOPGEN]) == tg, bar);
;             __builtin_amdgcn_fence(__ATOMIC_ACQUIRE, "agent");
;             xb_add(&bar[XB_XGEN(b.x)], 1u);
;             asm volatile("s_waitcnt vmcnt(0)" ::: "memory");
.LBB0_1648:
	s_or_b64 exec, exec, s[10:11]
	s_and_saveexec_b64 s[8:9], s[18:19]
	s_cbranch_execz .LBB0_1650
	v_mov_b32_e32 v4, 1
	global_atomic_add v[2:3], v4, off
.LBB0_1650:
	s_or_b64 exec, exec, s[8:9]
	s_mov_b64 s[8:9], exec
	v_mbcnt_lo_u32_b32 v2, s8, 0
	v_mbcnt_hi_u32_b32 v2, s9, v2
	s_mov_b32 s17, 0
	v_cmp_eq_u32_e32 vcc, 0, v2
	s_waitcnt vmcnt(0)
	s_and_saveexec_b64 s[10:11], vcc
	s_cbranch_execz .LBB0_1652
	s_add_i32 s16, s36, 0x900
	s_lshl_b64 s[16:17], s[16:17], 2
	s_add_u32 s16, s34, s16
	s_addc_u32 s17, s35, s17
	s_bcnt1_i32_b64 s8, s[8:9]
	v_mov_b32_e32 v2, 0
	v_mov_b32_e32 v3, s8

; __device__ __forceinline__ unsigned xb_ld(unsigned* p)              { return __hip_atomic_load(p, __ATOMIC_RELAXED, __HIP_MEMORY_SCOPE_AGENT); }
; __device__ __forceinline__ unsigned xb_add(unsigned* p, unsigned v) { return __hip_atomic_fetch_add(p, v, __ATOMIC_RELAXED, __HIP_MEMORY_SCOPE_AGENT); }
; #define XB_SPIN(cond, bar) do { unsigned _sp = 0; while (cond) { __builtin_amdgcn_s_sleep(1); \
;     if ((++_sp & 255u) == 0u) { if (xb_ld(&(bar)[XB_TMO])) break; if (_sp > XB_SPIN_CAP) { atomicAdd(&(bar)[XB_TMO], 1u); break; } } } } while (0)
; __device__ __forceinline__ void xcd_barrier(const XcdBarrier& b) {
;     ...
;             const unsigned og = xb_add(&bar[XB_TOP], 1u);
;             const unsigned tg = og / nx;
;             if (og + 1u == (tg + 1u) * nx) xb_add(&bar[XB_TOPGEN], 1u);
;             else XB_SPIN(xb_ld(&bar[XB_TOPGEN]) == tg, bar);
;             __builtin_amdgcn_fence(__ATOMIC_ACQUIRE, "agent");
;             xb_add(&bar[XB_XGEN(b.x)], 1u);
;             asm volatile("s_waitcnt vmcnt(0)" ::: "memory");
.LBB0_1794:
	s_or_b64 exec, exec, s[8:9]
	s_and_saveexec_b64 s[6:7], s[12:13]
	s_cbranch_execz .LBB0_1796
	v_mov_b32_e32 v4, 1
	global_atomic_add v[2:3], v4, off
.LBB0_1796:
	s_or_b64 exec, exec, s[6:7]
	s_mov_b64 s[6:7], exec
	v_mbcnt_lo_u32_b32 v2, s6, 0
	v_mbcnt_hi_u32_b32 v2, s7, v2
	s_mov_b32 s11, 0
	v_cmp_eq_u32_e32 vcc, 0, v2
	s_waitcnt vmcnt(0)
	s_and_saveexec_b64 s[8:9], vcc
	s_cbranch_execz .LBB0_1798
	s_add_i32 s10, s28, 0x900
	s_lshl_b64 s[10:11], s[10:11], 2
	s_add_u32 s10, s26, s10
	s_addc_u32 s11, s27, s11
	s_bcnt1_i32_b64 s6, s[6:7]
	v_mov_b32_e32 v2, 0
	v_mov_b32_e32 v3, s6

; __device__ __forceinline__ unsigned xb_ld(unsigned* p)              { return __hip_atomic_load(p, __ATOMIC_RELAXED, __HIP_MEMORY_SCOPE_AGENT); }
; __device__ __forceinline__ unsigned xb_add(unsigned* p, unsigned v) { return __hip_atomic_fetch_add(p, v, __ATOMIC_RELAXED, __HIP_MEMORY_SCOPE_AGENT); }
; #define XB_SPIN(cond, bar) do { unsigned _sp = 0; while (cond) { __builtin_amdgcn_s_sleep(1); \
;     if ((++_sp & 255u) == 0u) { if (xb_ld(&(bar)[XB_TMO])) break; if (_sp > XB_SPIN_CAP) { atomicAdd(&(bar)[XB_TMO], 1u); break; } } } } while (0)
; __device__ __forceinline__ void xcd_barrier(const XcdBarrier& b) {
;     ...
;             const unsigned og = xb_add(&bar[XB_TOP], 1u);
;             const unsigned tg = og / nx;
;             if (og + 1u == (tg + 1u) * nx) xb_add(&bar[XB_TOPGEN], 1u);
;             else XB_SPIN(xb_ld(&bar[XB_TOPGEN]) == tg, bar);
;             __builtin_amdgcn_fence(__ATOMIC_ACQUIRE, "agent");
;             xb_add(&bar[XB_XGEN(b.x)], 1u);
;             asm volatile("s_waitcnt vmcnt(0)" ::: "memory");
.LBB0_1929:
	s_or_b64 exec, exec, s[8:9]
	s_and_saveexec_b64 s[6:7], s[12:13]
	s_cbranch_execz .LBB0_1931
	v_mov_b32_e32 v4, 1
	global_atomic_add v[2:3], v4, off
.LBB0_1931:
	s_or_b64 exec, exec, s[6:7]
	s_mov_b64 s[6:7], exec
	v_mbcnt_lo_u32_b32 v2, s6, 0
	v_mbcnt_hi_u32_b32 v2, s7, v2
	s_mov_b32 s11, 0
	v_cmp_eq_u32_e32 vcc, 0, v2
	s_waitcnt vmcnt(0)
	s_and_saveexec_b64 s[8:9], vcc
	s_cbranch_execz .LBB0_1933
	s_add_i32 s10, s28, 0x900
	s_lshl_b64 s[10:11], s[10:11], 2
	s_add_u32 s10, s26, s10
	s_addc_u32 s11, s27, s11
	s_bcnt1_i32_b64 s6, s[6:7]
	v_mov_b32_e32 v2, 0
	v_mov_b32_e32 v3, s6

; __device__ __forceinline__ unsigned xb_ld(unsigned* p)              { return __hip_atomic_load(p, __ATOMIC_RELAXED, __HIP_MEMORY_SCOPE_AGENT); }
; __device__ __forceinline__ unsigned xb_add(unsigned* p, unsigned v) { return __hip_atomic_fetch_add(p, v, __ATOMIC_RELAXED, __HIP_MEMORY_SCOPE_AGENT); }
; #define XB_SPIN(cond, bar) do { unsigned _sp = 0; while (cond) { __builtin_amdgcn_s_sleep(1); \
;     if ((++_sp & 255u) == 0u) { if (xb_ld(&(bar)[XB_TMO])) break; if (_sp > XB_SPIN_CAP) { atomicAdd(&(bar)[XB_TMO], 1u); break; } } } } while (0)
; __device__ __forceinline__ void xcd_barrier(const XcdBarrier& b) {
;     ...
;             const unsigned og = xb_add(&bar[XB_TOP], 1u);
;             const unsigned tg = og / nx;
;             if (og + 1u == (tg + 1u) * nx) xb_add(&bar[XB_TOPGEN], 1u);
;             else XB_SPIN(xb_ld(&bar[XB_TOPGEN]) == tg, bar);
;             __builtin_amdgcn_fence(__ATOMIC_ACQUIRE, "agent");
;             xb_add(&bar[XB_XGEN(b.x)], 1u);
;             asm volatile("s_waitcnt vmcnt(0)" ::: "memory");
.LBB0_2100:
	s_or_b64 exec, exec, s[8:9]
	s_and_saveexec_b64 s[6:7], s[12:13]
	s_cbranch_execz .LBB0_2102
	v_mov_b32_e32 v4, 1
	global_atomic_add v[2:3], v4, off
.LBB0_2102:
	s_or_b64 exec, exec, s[6:7]
	s_mov_b64 s[6:7], exec
	v_mbcnt_lo_u32_b32 v2, s6, 0
	v_mbcnt_hi_u32_b32 v2, s7, v2
	s_mov_b32 s11, 0
	v_cmp_eq_u32_e32 vcc, 0, v2
	s_waitcnt vmcnt(0)
	s_and_saveexec_b64 s[8:9], vcc
	s_cbranch_execz .LBB0_2104
	s_add_i32 s10, s28, 0x900
	s_lshl_b64 s[10:11], s[10:11], 2
	s_add_u32 s10, s26, s10
	s_addc_u32 s11, s27, s11
	s_bcnt1_i32_b64 s6, s[6:7]
	v_mov_b32_e32 v2, 0
	v_mov_b32_e32 v3, s6

; __device__ __forceinline__ unsigned xb_ld(unsigned* p)              { return __hip_atomic_load(p, __ATOMIC_RELAXED, __HIP_MEMORY_SCOPE_AGENT); }
; __device__ __forceinline__ unsigned xb_add(unsigned* p, unsigned v) { return __hip_atomic_fetch_add(p, v, __ATOMIC_RELAXED, __HIP_MEMORY_SCOPE_AGENT); }
; #define XB_SPIN(cond, bar) do { unsigned _sp = 0; while (cond) { __builtin_amdgcn_s_sleep(1); \
;     if ((++_sp & 255u) == 0u) { if (xb_ld(&(bar)[XB_TMO])) break; if (_sp > XB_SPIN_CAP) { atomicAdd(&(bar)[XB_TMO], 1u); break; } } } } while (0)
; __device__ __forceinline__ void xcd_barrier(const XcdBarrier& b) {
;     ...
;             const unsigned og = xb_add(&bar[XB_TOP], 1u);
;             const unsigned tg = og / nx;
;             if (og + 1u == (tg + 1u) * nx) xb_add(&bar[XB_TOPGEN], 1u);
;             else XB_SPIN(xb_ld(&bar[XB_TOPGEN]) == tg, bar);
;             __builtin_amdgcn_fence(__ATOMIC_ACQUIRE, "agent");
;             xb_add(&bar[XB_XGEN(b.x)], 1u);
;             asm volatile("s_waitcnt vmcnt(0)" ::: "memory");
.LBB0_2219:
	s_or_b64 exec, exec, s[8:9]
	s_and_saveexec_b64 s[6:7], s[12:13]
	s_cbranch_execz .LBB0_2221
	v_mov_b32_e32 v4, 1
	global_atomic_add v[2:3], v4, off
.LBB0_2221:
	s_or_b64 exec, exec, s[6:7]
	s_mov_b64 s[6:7], exec
	v_mbcnt_lo_u32_b32 v2, s6, 0
	v_mbcnt_hi_u32_b32 v2, s7, v2
	s_mov_b32 s11, 0
	v_cmp_eq_u32_e32 vcc, 0, v2
	s_waitcnt vmcnt(0)
	s_and_saveexec_b64 s[8:9], vcc
	s_cbranch_execz .LBB0_2223
	s_add_i32 s10, s28, 0x900
	s_lshl_b64 s[10:11], s[10:11], 2
	s_add_u32 s10, s26, s10
	s_addc_u32 s11, s27, s11
	s_bcnt1_i32_b64 s6, s[6:7]
	v_mov_b32_e32 v2, 0
	v_mov_b32_e32 v3, s6

; __device__ __forceinline__ unsigned xb_ld(unsigned* p)              { return __hip_atomic_load(p, __ATOMIC_RELAXED, __HIP_MEMORY_SCOPE_AGENT); }
; __device__ __forceinline__ unsigned xb_add(unsigned* p, unsigned v) { return __hip_atomic_fetch_add(p, v, __ATOMIC_RELAXED, __HIP_MEMORY_SCOPE_AGENT); }
; #define XB_SPIN(cond, bar) do { unsigned _sp = 0; while (cond) { __builtin_amdgcn_s_sleep(1); \
;     if ((++_sp & 255u) == 0u) { if (xb_ld(&(bar)[XB_TMO])) break; if (_sp > XB_SPIN_CAP) { atomicAdd(&(bar)[XB_TMO], 1u); break; } } } } while (0)
; __device__ __forceinline__ void xcd_barrier(const XcdBarrier& b) {
;     ...
;             const unsigned og = xb_add(&bar[XB_TOP], 1u);
;             const unsigned tg = og / nx;
;             if (og + 1u == (tg + 1u) * nx) xb_add(&bar[XB_TOPGEN], 1u);
;             else XB_SPIN(xb_ld(&bar[XB_TOPGEN]) == tg, bar);
;             __builtin_amdgcn_fence(__ATOMIC_ACQUIRE, "agent");
;             xb_add(&bar[XB_XGEN(b.x)], 1u);
;             asm volatile("s_waitcnt vmcnt(0)" ::: "memory");
.LBB0_2500:
	s_or_b64 exec, exec, s[8:9]
	s_and_saveexec_b64 s[6:7], s[12:13]
	s_cbranch_execz .LBB0_2502
	v_mov_b32_e32 v4, 1
	global_atomic_add v[2:3], v4, off
.LBB0_2502:
	s_or_b64 exec, exec, s[6:7]
	s_mov_b64 s[6:7], exec
	v_mbcnt_lo_u32_b32 v2, s6, 0
	v_mbcnt_hi_u32_b32 v2, s7, v2
	s_mov_b32 s11, 0
	v_cmp_eq_u32_e32 vcc, 0, v2
	s_waitcnt vmcnt(0)
	s_and_saveexec_b64 s[8:9], vcc
	s_cbranch_execz .LBB0_2504
	s_add_i32 s10, s28, 0x900
	s_lshl_b64 s[10:11], s[10:11], 2
	s_add_u32 s10, s26, s10
	s_addc_u32 s11, s27, s11
	s_bcnt1_i32_b64 s6, s[6:7]
	v_mov_b32_e32 v2, 0
	v_mov_b32_e32 v3, s6

; __device__ __forceinline__ unsigned xb_ld(unsigned* p)              { return __hip_atomic_load(p, __ATOMIC_RELAXED, __HIP_MEMORY_SCOPE_AGENT); }
; __device__ __forceinline__ unsigned xb_add(unsigned* p, unsigned v) { return __hip_atomic_fetch_add(p, v, __ATOMIC_RELAXED, __HIP_MEMORY_SCOPE_AGENT); }
; #define XB_SPIN(cond, bar) do { unsigned _sp = 0; while (cond) { __builtin_amdgcn_s_sleep(1); \
;     if ((++_sp & 255u) == 0u) { if (xb_ld(&(bar)[XB_TMO])) break; if (_sp > XB_SPIN_CAP) { atomicAdd(&(bar)[XB_TMO], 1u); break; } } } } while (0)
; __device__ __forceinline__ void xcd_barrier(const XcdBarrier& b) {
;     ...
;             const unsigned og = xb_add(&bar[XB_TOP], 1u);
;             const unsigned tg = og / nx;
;             if (og + 1u == (tg + 1u) * nx) xb_add(&bar[XB_TOPGEN], 1u);
;             else XB_SPIN(xb_ld(&bar[XB_TOPGEN]) == tg, bar);
;             __builtin_amdgcn_fence(__ATOMIC_ACQUIRE, "agent");
;             xb_add(&bar[XB_XGEN(b.x)], 1u);
;             asm volatile("s_waitcnt vmcnt(0)" ::: "memory");
.LBB0_3089:
	s_or_b64 exec, exec, s[8:9]
	s_and_saveexec_b64 s[6:7], s[12:13]
	s_cbranch_execz .LBB0_3091
	v_mov_b32_e32 v4, 1
	global_atomic_add v[2:3], v4, off
.LBB0_3091:
	s_or_b64 exec, exec, s[6:7]
	s_mov_b64 s[6:7], exec
	v_mbcnt_lo_u32_b32 v2, s6, 0
	v_mbcnt_hi_u32_b32 v2, s7, v2
	s_mov_b32 s11, 0
	v_cmp_eq_u32_e32 vcc, 0, v2
	s_waitcnt vmcnt(0)
	s_and_saveexec_b64 s[8:9], vcc
	s_cbranch_execz .LBB0_3093
	s_add_i32 s10, s28, 0x900
	s_lshl_b64 s[10:11], s[10:11], 2
	s_add_u32 s10, s26, s10
	s_addc_u32 s11, s27, s11
	s_bcnt1_i32_b64 s6, s[6:7]
	v_mov_b32_e32 v2, 0
	v_mov_b32_e32 v3, s6

; __device__ __forceinline__ unsigned xb_ld(unsigned* p)              { return __hip_atomic_load(p, __ATOMIC_RELAXED, __HIP_MEMORY_SCOPE_AGENT); }
; __device__ __forceinline__ unsigned xb_add(unsigned* p, unsigned v) { return __hip_atomic_fetch_add(p, v, __ATOMIC_RELAXED, __HIP_MEMORY_SCOPE_AGENT); }
; #define XB_SPIN(cond, bar) do { unsigned _sp = 0; while (cond) { __builtin_amdgcn_s_sleep(1); \
;     if ((++_sp & 255u) == 0u) { if (xb_ld(&(bar)[XB_TMO])) break; if (_sp > XB_SPIN_CAP) { atomicAdd(&(bar)[XB_TMO], 1u); break; } } } } while (0)
; __device__ __forceinline__ void xcd_barrier(const XcdBarrier& b) {
;     ...
;         unsigned nloc = b.st[0], nx = b.st[1];
;         if (nloc == 0u) { xcd_barrier_complete(bar, b.x, nloc, nx); b.st[0] = nloc; b.st[1] = nx; }
;         const unsigned old = xb_add(&bar[XB_XSUB(b.x)], 1u);
;         const unsigned gen = old / nloc;
;         if (old + 1u == (gen + 1u) * nloc) {
;             __builtin_amdgcn_fence(__ATOMIC_RELEASE, "agent");
;             asm volatile("s_waitcnt vmcnt(0)" ::: "memory");
;             const unsigned og = xb_add(&bar[XB_TOP], 1u);
;             const unsigned tg = og / nx;
;             if (og + 1u == (tg + 1u) * nx) xb_add(&bar[XB_TOPGEN], 1u);
;             else XB_SPIN(xb_ld(&bar[XB_TOPGEN]) == tg, bar);
;             __builtin_amdgcn_fence(__ATOMIC_ACQUIRE, "agent");
;             xb_add(&bar[XB_XGEN(b.x)], 1u);
;             asm volatile("s_waitcnt vmcnt(0)" ::: "memory");
;         } else {
;             XB_SPIN(xb_ld(&bar[XB_XGEN(b.x)]) == gen, bar);
;             __builtin_amdgcn_fence(__ATOMIC_ACQUIRE, "agent");
;             asm volatile("s_waitcnt vmcnt(0)" ::: "memory");
.LBB0_3173:
	s_or_b64 exec, exec, s[10:11]
	v_cvt_f32_u32_e32 v6, v4
	s_waitcnt vmcnt(0)
	v_readfirstlane_b32 s8, v5
	v_sub_u32_e32 v5, 0, v4
	v_rcp_iflag_f32_e32 v6, v6
	v_add_u32_e32 v7, s8, v3
	v_mul_f32_e32 v6, 0x4f7ffffe, v6
	v_cvt_u32_f32_e32 v6, v6
	v_mul_lo_u32 v3, v5, v6
	v_mul_hi_u32 v3, v6, v3
	v_add_u32_e32 v3, v6, v3
	v_mul_hi_u32 v3, v7, v3
	v_mul_lo_u32 v5, v3, v4
	v_sub_u32_e32 v5, v7, v5
	v_add_u32_e32 v6, 1, v3
	v_cmp_ge_u32_e32 vcc, v5, v4
	s_nop 1
	v_cndmask_b32_e32 v3, v3, v6, vcc
	v_sub_u32_e32 v6, v5, v4
	v_cndmask_b32_e32 v5, v5, v6, vcc
	v_add_u32_e32 v6, 1, v3
	v_cmp_ge_u32_e32 vcc, v5, v4
	v_add_u32_e32 v5, 1, v7
	s_nop 0
	v_cndmask_b32_e32 v3, v3, v6, vcc
	v_mul_lo_u32 v6, v4, v3
	v_add_u32_e32 v4, v6, v4
	v_mad_u32_u24 v255, v3, v2, v2
	v_cmp_ne_u32_e32 vcc, v5, v4
	s_and_saveexec_b64 s[8:9], vcc
	s_xor_b64 s[8:9], exec, s[8:9]
	s_cbranch_execz .LBB0_3187
	buffer_inv sc1
	s_add_i32 s10, s30, 0x900
	s_mov_b32 s11, 0
	s_lshl_b64 s[10:11], s[10:11], 2
	s_add_u32 s16, s28, s10
	s_addc_u32 s17, s29, s11
	s_waitcnt lgkmcnt(0)
	v_mov_b32_e32 v2, 0
	global_load_dword v4, v2, s[16:17] sc1
	s_waitcnt vmcnt(0)
	v_cmp_lt_u32_e32 vcc, v4, v255
	s_and_saveexec_b64 s[10:11], vcc
	s_cbranch_execz .LBB0_3186
	s_add_u32 s14, s6, 0xc0200
	s_addc_u32 s15, s7, 0
	s_mov_b32 s31, 1
	s_mov_b64 s[18:19], 0
	s_branch .LBB0_3177

; __device__ __forceinline__ unsigned xb_ld(unsigned* p)              { return __hip_atomic_load(p, __ATOMIC_RELAXED, __HIP_MEMORY_SCOPE_AGENT); }
; #define XB_SPIN(cond, bar) do { unsigned _sp = 0; while (cond) { __builtin_amdgcn_s_sleep(1); \
;     if ((++_sp & 255u) == 0u) { if (xb_ld(&(bar)[XB_TMO])) break; if (_sp > XB_SPIN_CAP) { atomicAdd(&(bar)[XB_TMO], 1u); break; } } } } while (0)
; __device__ __forceinline__ void xcd_barrier(const XcdBarrier& b) {
;     ...
;             XB_SPIN(xb_ld(&bar[XB_XGEN(b.x)]) == gen, bar);
.LBB0_3179:
	global_load_dword v4, v2, s[16:17] sc1
	s_add_i32 s31, s31, 1
	s_mov_b64 s[24:25], -1
	s_waitcnt vmcnt(0)
	v_cmp_ge_u32_e32 vcc, v4, v255
	s_orn2_b64 s[22:23], vcc, exec
	s_branch .LBB0_3176

; __device__ __forceinline__ unsigned xb_ld(unsigned* p)              { return __hip_atomic_load(p, __ATOMIC_RELAXED, __HIP_MEMORY_SCOPE_AGENT); }
; __device__ __forceinline__ unsigned xb_add(unsigned* p, unsigned v) { return __hip_atomic_fetch_add(p, v, __ATOMIC_RELAXED, __HIP_MEMORY_SCOPE_AGENT); }
; #define XB_SPIN(cond, bar) do { unsigned _sp = 0; while (cond) { __builtin_amdgcn_s_sleep(1); \
;     if ((++_sp & 255u) == 0u) { if (xb_ld(&(bar)[XB_TMO])) break; if (_sp > XB_SPIN_CAP) { atomicAdd(&(bar)[XB_TMO], 1u); break; } } } } while (0)
; __device__ __forceinline__ void xcd_barrier(const XcdBarrier& b) {
;     ...
;         if (old + 1u == (gen + 1u) * nloc) {
;             __builtin_amdgcn_fence(__ATOMIC_RELEASE, "agent");
;             asm volatile("s_waitcnt vmcnt(0)" ::: "memory");
;             const unsigned og = xb_add(&bar[XB_TOP], 1u);
;             const unsigned tg = og / nx;
;             if (og + 1u == (tg + 1u) * nx) xb_add(&bar[XB_TOPGEN], 1u);
;             else XB_SPIN(xb_ld(&bar[XB_TOPGEN]) == tg, bar);
;             __builtin_amdgcn_fence(__ATOMIC_ACQUIRE, "agent");
;             xb_add(&bar[XB_XGEN(b.x)], 1u);
;             asm volatile("s_waitcnt vmcnt(0)" ::: "memory");
.LBB0_3190:
	s_or_b64 exec, exec, s[10:11]
	v_cvt_f32_u32_e32 v5, v2
	s_waitcnt vmcnt(0)
	v_readfirstlane_b32 s8, v4
	s_add_i32 s10, s30, 0x900
	s_mov_b32 s11, 0
	s_lshl_b64 s[10:11], s[10:11], 2
	s_add_u32 s10, s28, s10
	s_addc_u32 s11, s29, s11
	v_rcp_iflag_f32_e32 v5, v5
	v_add_u32_e32 v3, s8, v3
	v_add_u32_e32 v6, 1, v3
	s_mov_b64 s[14:15], -1
	v_mul_f32_e32 v4, 0x4f7ffffe, v5
	v_cvt_u32_f32_e32 v4, v4
	v_sub_u32_e32 v5, 0, v2
	v_mul_lo_u32 v5, v5, v4
	v_mul_hi_u32 v5, v4, v5
	v_add_u32_e32 v4, v4, v5
	v_mul_hi_u32 v4, v3, v4
	v_mul_lo_u32 v5, v4, v2
	v_sub_u32_e32 v3, v3, v5
	v_add_u32_e32 v7, 1, v4
	v_cmp_ge_u32_e32 vcc, v3, v2
	v_sub_u32_e32 v5, v3, v2
	s_nop 0
	v_cndmask_b32_e32 v4, v4, v7, vcc
	v_cndmask_b32_e32 v3, v3, v5, vcc
	v_add_u32_e32 v5, 1, v4
	v_cmp_ge_u32_e32 vcc, v3, v2
	s_nop 1
	v_cndmask_b32_e32 v4, v4, v5, vcc
	v_mul_lo_u32 v3, v2, v4
	v_add_u32_e32 v2, v3, v2
	v_cmp_eq_u32_e32 vcc, v2, v2
	v_mov_b64_e32 v[2:3], s[10:11]
	s_and_saveexec_b64 s[8:9], vcc
	s_cbranch_execz .LBB0_3202
	v_mov_b32_e32 v2, 0
	global_load_dword v3, v2, s[10:11] sc1
	s_mov_b64 s[18:19], 0
	s_waitcnt vmcnt(0)
	v_cmp_lt_u32_e32 vcc, v3, v255
	s_and_saveexec_b64 s[16:17], vcc
	s_cbranch_execz .LBB0_3201
	s_add_u32 s14, s6, 0xc0200
	s_addc_u32 s15, s7, 0
	s_mov_b32 s26, 1
	s_mov_b64 s[6:7], 0
	s_branch .LBB0_3194

; __device__ __forceinline__ unsigned xb_ld(unsigned* p)              { return __hip_atomic_load(p, __ATOMIC_RELAXED, __HIP_MEMORY_SCOPE_AGENT); }
; #define XB_SPIN(cond, bar) do { unsigned _sp = 0; while (cond) { __builtin_amdgcn_s_sleep(1); \
;     if ((++_sp & 255u) == 0u) { if (xb_ld(&(bar)[XB_TMO])) break; if (_sp > XB_SPIN_CAP) { atomicAdd(&(bar)[XB_TMO], 1u); break; } } } } while (0)
; __device__ __forceinline__ void xcd_barrier(const XcdBarrier& b) {
;     ...
;             else XB_SPIN(xb_ld(&bar[XB_TOPGEN]) == tg, bar);
.LBB0_3196:
	global_load_dword v3, v2, s[10:11] sc1
	s_add_i32 s26, s26, 1
	s_mov_b64 s[20:21], -1
	s_waitcnt vmcnt(0)
	v_cmp_ge_u32_e32 vcc, v3, v255
	s_orn2_b64 s[24:25], vcc, exec
	s_branch .LBB0_3193

; __device__ __forceinline__ unsigned xb_ld(unsigned* p)              { return __hip_atomic_load(p, __ATOMIC_RELAXED, __HIP_MEMORY_SCOPE_AGENT); }
; __device__ __forceinline__ unsigned xb_add(unsigned* p, unsigned v) { return __hip_atomic_fetch_add(p, v, __ATOMIC_RELAXED, __HIP_MEMORY_SCOPE_AGENT); }
; #define XB_SPIN(cond, bar) do { unsigned _sp = 0; while (cond) { __builtin_amdgcn_s_sleep(1); \
;     if ((++_sp & 255u) == 0u) { if (xb_ld(&(bar)[XB_TMO])) break; if (_sp > XB_SPIN_CAP) { atomicAdd(&(bar)[XB_TMO], 1u); break; } } } } while (0)
; __device__ __forceinline__ void xcd_barrier(const XcdBarrier& b) {
;     ...
;             const unsigned og = xb_add(&bar[XB_TOP], 1u);
;             const unsigned tg = og / nx;
;             if (og + 1u == (tg + 1u) * nx) xb_add(&bar[XB_TOPGEN], 1u);
;             else XB_SPIN(xb_ld(&bar[XB_TOPGEN]) == tg, bar);
;             __builtin_amdgcn_fence(__ATOMIC_ACQUIRE, "agent");
;             xb_add(&bar[XB_XGEN(b.x)], 1u);
;             asm volatile("s_waitcnt vmcnt(0)" ::: "memory");
.LBB0_3202:
	s_or_b64 exec, exec, s[8:9]
	s_and_saveexec_b64 s[6:7], s[14:15]
	s_cbranch_execz .LBB0_3204
	v_mov_b32_e32 v4, 1
	global_atomic_add v[2:3], v4, off
.LBB0_3204:
	s_or_b64 exec, exec, s[6:7]
	s_mov_b64 s[6:7], exec
	v_mbcnt_lo_u32_b32 v2, s6, 0
	v_mbcnt_hi_u32_b32 v2, s7, v2
	s_mov_b32 s11, 0
	v_cmp_eq_u32_e32 vcc, 0, v2
	s_waitcnt vmcnt(0)
	s_and_saveexec_b64 s[8:9], vcc
	s_cbranch_execz .LBB0_3206
	s_add_i32 s10, s30, 0x900
	s_lshl_b64 s[10:11], s[10:11], 2
	s_add_u32 s10, s28, s10
	s_addc_u32 s11, s29, s11
	s_bcnt1_i32_b64 s6, s[6:7]
	v_mov_b32_e32 v2, 0
	v_mov_b32_e32 v3, s6

; __device__ __forceinline__ unsigned xb_ld(unsigned* p)              { return __hip_atomic_load(p, __ATOMIC_RELAXED, __HIP_MEMORY_SCOPE_AGENT); }
; __device__ __forceinline__ unsigned xb_add(unsigned* p, unsigned v) { return __hip_atomic_fetch_add(p, v, __ATOMIC_RELAXED, __HIP_MEMORY_SCOPE_AGENT); }
; #define XB_SPIN(cond, bar) do { unsigned _sp = 0; while (cond) { __builtin_amdgcn_s_sleep(1); \
;     if ((++_sp & 255u) == 0u) { if (xb_ld(&(bar)[XB_TMO])) break; if (_sp > XB_SPIN_CAP) { atomicAdd(&(bar)[XB_TMO], 1u); break; } } } } while (0)
; __device__ __forceinline__ void xcd_barrier(const XcdBarrier& b) {
;     ...
;             const unsigned og = xb_add(&bar[XB_TOP], 1u);
;             const unsigned tg = og / nx;
;             if (og + 1u == (tg + 1u) * nx) xb_add(&bar[XB_TOPGEN], 1u);
;             else XB_SPIN(xb_ld(&bar[XB_TOPGEN]) == tg, bar);
;             __builtin_amdgcn_fence(__ATOMIC_ACQUIRE, "agent");
;             xb_add(&bar[XB_XGEN(b.x)], 1u);
;             asm volatile("s_waitcnt vmcnt(0)" ::: "memory");
.LBB0_3302:
	s_or_b64 exec, exec, s[8:9]
	s_and_saveexec_b64 s[6:7], s[12:13]
	s_cbranch_execz .LBB0_3304
	v_mov_b32_e32 v1, 1
	global_atomic_add v[2:3], v1, off
.LBB0_3304:
	s_or_b64 exec, exec, s[6:7]
	s_mov_b64 s[6:7], exec
	v_mbcnt_lo_u32_b32 v1, s6, 0
	v_mbcnt_hi_u32_b32 v1, s7, v1
	s_mov_b32 s11, 0
	v_cmp_eq_u32_e32 vcc, 0, v1
	s_waitcnt vmcnt(0)
	s_and_saveexec_b64 s[8:9], vcc
	s_cbranch_execz .LBB0_3306
	s_add_i32 s10, s28, 0x900
	s_lshl_b64 s[10:11], s[10:11], 2
	s_add_u32 s10, s26, s10
	s_addc_u32 s11, s27, s11
	s_bcnt1_i32_b64 s6, s[6:7]
	v_mov_b32_e32 v1, 0
	v_mov_b32_e32 v2, s6

; __device__ __forceinline__ unsigned xb_ld(unsigned* p)              { return __hip_atomic_load(p, __ATOMIC_RELAXED, __HIP_MEMORY_SCOPE_AGENT); }
; __device__ __forceinline__ unsigned xb_add(unsigned* p, unsigned v) { return __hip_atomic_fetch_add(p, v, __ATOMIC_RELAXED, __HIP_MEMORY_SCOPE_AGENT); }
; #define XB_SPIN(cond, bar) do { unsigned _sp = 0; while (cond) { __builtin_amdgcn_s_sleep(1); \
;     if ((++_sp & 255u) == 0u) { if (xb_ld(&(bar)[XB_TMO])) break; if (_sp > XB_SPIN_CAP) { atomicAdd(&(bar)[XB_TMO], 1u); break; } } } } while (0)
; __device__ __forceinline__ void xcd_barrier(const XcdBarrier& b) {
;     ...
;             const unsigned og = xb_add(&bar[XB_TOP], 1u);
;             const unsigned tg = og / nx;
;             if (og + 1u == (tg + 1u) * nx) xb_add(&bar[XB_TOPGEN], 1u);
;             else XB_SPIN(xb_ld(&bar[XB_TOPGEN]) == tg, bar);
;             __builtin_amdgcn_fence(__ATOMIC_ACQUIRE, "agent");
;             xb_add(&bar[XB_XGEN(b.x)], 1u);
;             asm volatile("s_waitcnt vmcnt(0)" ::: "memory");
.LBB0_3394:
	s_or_b64 exec, exec, s[8:9]
	s_and_saveexec_b64 s[6:7], s[12:13]
	s_cbranch_execz .LBB0_3396
	v_mov_b32_e32 v1, 1
	global_atomic_add v[2:3], v1, off
.LBB0_3396:
	s_or_b64 exec, exec, s[6:7]
	s_mov_b64 s[6:7], exec
	v_mbcnt_lo_u32_b32 v1, s6, 0
	v_mbcnt_hi_u32_b32 v1, s7, v1
	s_mov_b32 s11, 0
	v_cmp_eq_u32_e32 vcc, 0, v1
	s_waitcnt vmcnt(0)
	s_and_saveexec_b64 s[8:9], vcc
	s_cbranch_execz .LBB0_3398
	s_add_i32 s10, s28, 0x900
	s_lshl_b64 s[10:11], s[10:11], 2
	s_add_u32 s10, s26, s10
	s_addc_u32 s11, s27, s11
	s_bcnt1_i32_b64 s6, s[6:7]
	v_mov_b32_e32 v1, 0
	v_mov_b32_e32 v2, s6

; __global__ void __launch_bounds__(NT, 2) mega(Args a_unused) {
;     extern __shared__ __attribute__((aligned(16))) unsigned char lds[];
	.amdhsa_kernel _Z4mega4Args
		.amdhsa_group_segment_fixed_size 0
		.amdhsa_private_segment_fixed_size 0
		.amdhsa_kernarg_size 512
		.amdhsa_user_sgpr_count 2
		.amdhsa_user_sgpr_dispatch_ptr 0
		.amdhsa_user_sgpr_queue_ptr 0
		.amdhsa_user_sgpr_kernarg_segment_ptr 1
		.amdhsa_user_sgpr_dispatch_id 0
		.amdhsa_user_sgpr_kernarg_preload_length 0
		.amdhsa_user_sgpr_kernarg_preload_offset 0
		.amdhsa_user_sgpr_private_segment_size 0
		.amdhsa_uses_dynamic_stack 0
		.amdhsa_enable_private_segment 0
		.amdhsa_system_sgpr_workgroup_id_x 1
		.amdhsa_system_sgpr_workgroup_id_y 0
		.amdhsa_system_sgpr_workgroup_id_z 0
		.amdhsa_system_sgpr_workgroup_info 0
		.amdhsa_system_vgpr_workitem_id 0
		.amdhsa_next_free_vgpr 256
		.amdhsa_next_free_sgpr 102
		.amdhsa_accum_offset 256
		.amdhsa_reserve_vcc 1
		.amdhsa_float_round_mode_32 0
		.amdhsa_float_round_mode_16_64 0
		.amdhsa_float_denorm_mode_32 3
		.amdhsa_float_denorm_mode_16_64 3
		.amdhsa_dx10_clamp 1
		.amdhsa_ieee_mode 1
		.amdhsa_fp16_overflow 0
		.amdhsa_tg_split 0
		.amdhsa_exception_fp_ieee_invalid_op 0
		.amdhsa_exception_fp_denorm_src 0
		.amdhsa_exception_fp_ieee_div_zero 0
		.amdhsa_exception_fp_ieee_overflow 0
		.amdhsa_exception_fp_ieee_underflow 0
		.amdhsa_exception_fp_ieee_inexact 0
		.amdhsa_exception_int_div_zero 0
	.end_amdhsa_kernel

; __global__ void __launch_bounds__(NT, 2) mega(Args a_unused) {
amdhsa.kernels:
  - .agpr_count:     0
    .args:
      - .offset:         0
        .size:           256
        .value_kind:     by_value
      - .offset:         256
        .size:           4
        .value_kind:     hidden_block_count_x
      - .offset:         260
        .size:           4
        .value_kind:     hidden_block_count_y
      - .offset:         264
        .size:           4
        .value_kind:     hidden_block_count_z
      - .offset:         268
        .size:           2
        .value_kind:     hidden_group_size_x
      - .offset:         270
        .size:           2
        .value_kind:     hidden_group_size_y
      - .offset:         272
        .size:           2
        .value_kind:     hidden_group_size_z
      - .offset:         274
        .size:           2
        .value_kind:     hidden_remainder_x
      - .offset:         276
        .size:           2
        .value_kind:     hidden_remainder_y
      - .offset:         278
        .size:           2
        .value_kind:     hidden_remainder_z
      - .offset:         296
        .size:           8
        .value_kind:     hidden_global_offset_x
      - .offset:         304
        .size:           8
        .value_kind:     hidden_global_offset_y
      - .offset:         312
        .size:           8
        .value_kind:     hidden_global_offset_z
      - .offset:         320
        .size:           2
        .value_kind:     hidden_grid_dims
      - .offset:         376
        .size:           4
        .value_kind:     hidden_dynamic_lds_size
    .group_segment_fixed_size: 0
    .kernarg_segment_align: 8
    .kernarg_segment_size: 512
    .language:       OpenCL C
    .language_version:
      - 2
      - 0
    .max_flat_workgroup_size: 512
    .name:           _Z4mega4Args
    .private_segment_fixed_size: 0
    .sgpr_count: 108
    .sgpr_spill_count: 7
    .symbol:         _Z4mega4Args.kd
    .uniform_work_group_size: 1
    .uses_dynamic_stack: false
    .vgpr_count:     256
    .vgpr_spill_count: 0
    .wavefront_size: 64
